# best5 + grid barrier: non-leader workgroups poll the cross-XCD release word directly instead of waiting for their XCD leader to relay it (one hop less per barrier)
# baseline (speedup 1.0000x reference)
; __device__ __forceinline__ unsigned xb_ld(unsigned* p)              { return __hip_atomic_load(p, __ATOMIC_RELAXED, __HIP_MEMORY_SCOPE_AGENT); }
; __device__ __forceinline__ unsigned xb_add(unsigned* p, unsigned v) { return __hip_atomic_fetch_add(p, v, __ATOMIC_RELAXED, __HIP_MEMORY_SCOPE_AGENT); }
; #define XB_SPIN(cond, bar) do { unsigned _sp = 0; while (cond) { __builtin_amdgcn_s_sleep(1); \
;     if ((++_sp & 255u) == 0u) { if (xb_ld(&(bar)[XB_TMO])) break; if (_sp > XB_SPIN_CAP) { atomicAdd(&(bar)[XB_TMO], 1u); break; } } } } while (0)
; __device__ __forceinline__ void xcd_barrier(const XcdBarrier& b) {
;     ...
;         const unsigned old = xb_add(&bar[XB_XSUB(b.x)], 1u);
;         const unsigned gen = old / nloc;
;         if (old + 1u == (gen + 1u) * nloc) {
;             __builtin_amdgcn_fence(__ATOMIC_RELEASE, "agent");
;             asm volatile("s_waitcnt vmcnt(0)" ::: "memory");
;             const unsigned og = xb_add(&bar[XB_TOP], 1u);
;             const unsigned tg = og / nx;
;             if (og + 1u == (tg + 1u) * nx) xb_add(&bar[XB_TOPGEN], 1u);
;             else XB_SPIN(xb_ld(&bar[XB_TOPGEN]) == tg, bar);
;             __builtin_amdgcn_fence(__ATOMIC_ACQUIRE, "agent");
;             xb_add(&bar[XB_XGEN(b.x)], 1u);
;             asm volatile("s_waitcnt vmcnt(0)" ::: "memory");
;         } else {
;             XB_SPIN(xb_ld(&bar[XB_XGEN(b.x)]) == gen, bar);
.LBB0_538:
	s_or_b64 exec, exec, s[22:23]
	v_cvt_f32_u32_e32 v4, v2
	s_waitcnt vmcnt(0)
	v_readfirstlane_b32 s0, v3
	v_sub_u32_e32 v3, 0, v2
	v_rcp_iflag_f32_e32 v4, v4
	v_add_u32_e32 v5, s0, v1
	v_mul_f32_e32 v4, 0x4f7ffffe, v4
	v_cvt_u32_f32_e32 v4, v4
	v_mul_lo_u32 v1, v3, v4
	v_mul_hi_u32 v1, v4, v1
	v_add_u32_e32 v1, v4, v1
	v_mul_hi_u32 v1, v5, v1
	v_mul_lo_u32 v3, v1, v2
	v_sub_u32_e32 v3, v5, v3
	v_add_u32_e32 v4, 1, v1
	v_cmp_ge_u32_e32 vcc, v3, v2
	s_nop 1
	v_cndmask_b32_e32 v1, v1, v4, vcc
	v_sub_u32_e32 v4, v3, v2
	v_cndmask_b32_e32 v3, v3, v4, vcc
	v_add_u32_e32 v4, 1, v1
	v_cmp_ge_u32_e32 vcc, v3, v2
	v_add_u32_e32 v3, 1, v5
	s_nop 0
	v_cndmask_b32_e32 v1, v1, v4, vcc
	v_mul_lo_u32 v4, v2, v1
	v_add_u32_e32 v2, v4, v2
	v_cmp_ne_u32_e32 vcc, v3, v2
	s_and_saveexec_b64 s[16:17], vcc
	s_xor_b64 s[22:23], exec, s[16:17]
	s_cbranch_execz .LBB0_553
	v_readlane_b32 s16, v252, 23
	v_readlane_b32 s17, v252, 24
	s_waitcnt lgkmcnt(0)
	s_nop 3
	global_load_dword v0, v97, s[16:17] sc1
	s_waitcnt vmcnt(0)
	v_cmp_eq_u32_e32 vcc, v0, v1
	s_and_saveexec_b64 s[38:39], vcc
	s_cbranch_execz .LBB0_552
	s_mov_b32 s0, 1
	s_mov_b64 s[40:41], 0
	s_branch .LBB0_542

; __device__ __forceinline__ unsigned xb_ld(unsigned* p)              { return __hip_atomic_load(p, __ATOMIC_RELAXED, __HIP_MEMORY_SCOPE_AGENT); }
; #define XB_SPIN(cond, bar) do { unsigned _sp = 0; while (cond) { __builtin_amdgcn_s_sleep(1); \
;     if ((++_sp & 255u) == 0u) { if (xb_ld(&(bar)[XB_TMO])) break; if (_sp > XB_SPIN_CAP) { atomicAdd(&(bar)[XB_TMO], 1u); break; } } } } while (0)
; __device__ __forceinline__ void xcd_barrier(const XcdBarrier& b) {
;     ...
;             XB_SPIN(xb_ld(&bar[XB_XGEN(b.x)]) == gen, bar);
.LBB0_544:
	v_readlane_b32 s16, v252, 23
	v_readlane_b32 s17, v252, 24
	s_add_i32 s0, s0, 1
	s_mov_b64 s[46:47], -1
	s_nop 2
	global_load_dword v0, v97, s[16:17] sc1
	s_waitcnt vmcnt(0)
	v_cmp_ne_u32_e32 vcc, v0, v1
	s_orn2_b64 s[44:45], vcc, exec
	s_branch .LBB0_541
